# attnA: second K fragment batch read earlier (after the last PV MFMA / first S MFMA)
# baseline (speedup 1.0000x reference)
; #define FA_SB() __builtin_amdgcn_sched_barrier(0)
; #define FA_PVM(G) do { o[(G) & 3] = __builtin_amdgcn_mfma_f32_32x32x16_bf16(__builtin_bit_cast(bf16x8, vr[(G) % 3]), __builtin_bit_cast(bf16x8, PWC[(G) >> 2]), o[(G) & 3], 0, 0, 0); if ((G) + 3 < 16) vr[(G) % 3] = FA_VFRAG((G) + 3); } while (0)
; #define FA_EXP2(J, PX, R) do { const float e0_ = __builtin_amdgcn_exp2f(PX[R]), e1_ = __builtin_amdgcn_exp2f(PX[(R) + 1]); ps += e0_; ps += e1_; PWN[(J) >> 2][(J) & 3] = cvtpk(e0_, e1_); } while (0)
; __device__ __forceinline__ void attn_unit_a(FLAS unsigned char* lds, const Unit u) {
;     ...
;         for (int g = 8; g < 16; ++g) { FA_PVM(g); FA_EXP2(g - 8, pC0, 2 * (g - 8));
;             if (g == 12) { kf[0] = FA_KF(0, 0); kf[1] = FA_KF(0, 1); kf[2] = FA_KF(1, 0); kf[3] = FA_KF(1, 1); }
;             FA_SB(); }
;         float cbN; bool ziN; const int inx = (i + 1 < NT) ? i + 1 : NT - 1;
;         FA_BIAS(inx, pN0, pN1, cbN, ziN);
.LBB0_442:
	s_waitcnt lgkmcnt(2)
	v_mfma_f32_32x32x16_bf16 v[48:63], v[136:139], v[192:195], v[48:63]
	ds_read_b128 v[136:139], v200 offset:30272
	v_exp_f32_e32 v96, v96
	v_exp_f32_e32 v97, v97
	s_waitcnt lgkmcnt(2)
	v_mfma_f32_32x32x16_bf16 v[32:47], v[128:131], v[192:195], v[32:47]
	ds_read_b128 v[128:131], v200 offset:16480
	v_exp_f32_e32 v98, v98
	v_exp_f32_e32 v99, v99
	v_add_f32_e32 v212, v96, v212
	v_add_f32_e32 v212, v97, v212
	s_waitcnt lgkmcnt(2)
	v_mfma_f32_32x32x16_bf16 v[16:31], v[132:135], v[192:195], v[16:31]
	ds_read_b128 v[132:135], v200 offset:21088
	v_exp_f32_e32 v100, v100
	v_exp_f32_e32 v101, v101
	v_add_f32_e32 v212, v98, v212
	v_add_f32_e32 v212, v99, v212
	s_waitcnt lgkmcnt(2)
	v_mfma_f32_32x32x16_bf16 v[0:15], v[136:139], v[192:195], v[0:15]
	ds_read_b128 v[136:139], v200 offset:25696
	v_exp_f32_e32 v102, v102
	v_exp_f32_e32 v103, v103
	v_add_f32_e32 v212, v100, v212
	v_add_f32_e32 v212, v101, v212
	s_waitcnt lgkmcnt(2)
	v_mfma_f32_32x32x16_bf16 v[48:63], v[128:131], v[188:191], v[48:63]
	ds_read_b128 v[128:131], v200 offset:30304
	ds_read_b128 v[204:207], v247 offset:8192
	ds_read_b128 v[200:203], v247 offset:8704
	ds_read_b128 v[196:199], v248 offset:8192
	ds_read_b128 v[192:195], v248 offset:8704
	v_exp_f32_e32 v104, v104
	v_exp_f32_e32 v105, v105
	v_add_f32_e32 v212, v102, v212
	v_add_f32_e32 v212, v103, v212
	s_waitcnt lgkmcnt(6)
	v_mfma_f32_32x32x16_bf16 v[32:47], v[132:135], v[188:191], v[32:47]
	v_exp_f32_e32 v106, v106
	v_exp_f32_e32 v107, v107
	v_add_f32_e32 v212, v104, v212
	v_add_f32_e32 v212, v105, v212
	s_waitcnt lgkmcnt(5)
	v_mfma_f32_32x32x16_bf16 v[16:31], v[136:139], v[188:191], v[16:31]
	v_exp_f32_e32 v108, v108
	v_exp_f32_e32 v109, v109
	v_add_f32_e32 v212, v106, v212
	v_add_f32_e32 v212, v107, v212
	s_waitcnt lgkmcnt(4)
	v_mfma_f32_32x32x16_bf16 v[0:15], v[128:131], v[188:191], v[0:15]
	v_exp_f32_e32 v110, v110
	v_exp_f32_e32 v111, v111
	v_add_f32_e32 v212, v108, v212
	v_add_f32_e32 v212, v109, v212
	ds_read_b128 v[128:131], v249 offset:8192
	ds_read_b128 v[132:135], v249 offset:8704
	s_sub_i32 s12, s48, 31
	s_cmpk_lt_i32 s12, 0x22f
	s_cbranch_scc0 .Lz_plus_e
	s_cmpk_gt_i32 s48, 0xfd92
	s_cbranch_scc1 .Lgather_e
	v_sub_f32_e32 v142, s100, v211
	s_branch .Lz_chk_e

; #define FLAS __attribute__((address_space(3)))
; #define FA_SB() __builtin_amdgcn_sched_barrier(0)
; #define FA_EXP2(J, PX, R) do { const float e0_ = __builtin_amdgcn_exp2f(PX[R]), e1_ = __builtin_amdgcn_exp2f(PX[(R) + 1]); ps += e0_; ps += e1_; PWN[(J) >> 2][(J) & 3] = cvtpk(e0_, e1_); } while (0)
; __device__ __forceinline__ void attn_unit_a(FLAS unsigned char* lds, const Unit u) {
;     ...
;         FA_BIAS(inx, pN0, pN1, cbN, ziN);
;         FA_SB();
;         if (ziN) { pN0 = __builtin_amdgcn_mfma_f32_32x32x16_bf16(kf[0], qr[0], z16, 0, 0, 0); FA_EXP2(8, pC1, 0); FA_SB(); pN1 = __builtin_amdgcn_mfma_f32_32x32x16_bf16(kf[1], qr[0], z16, 0, 0, 0); }
;         else { pN0 = __builtin_amdgcn_mfma_f32_32x32x16_bf16(kf[0], qr[0], pN0, 0, 0, 0); FA_EXP2(8, pC1, 0); FA_SB(); pN1 = __builtin_amdgcn_mfma_f32_32x32x16_bf16(kf[1], qr[0], pN1, 0, 0, 0); }
;         kf[0] = FA_KF(2, 0); kf[1] = FA_KF(2, 1); FA_EXP2(9, pC1, 2); FA_SB();
;         pN0 = __builtin_amdgcn_mfma_f32_32x32x16_bf16(kf[2], qr[1], pN0, 0, 0, 0); FA_EXP2(10, pC1, 4); FA_SB();
;         pN1 = __builtin_amdgcn_mfma_f32_32x32x16_bf16(kf[3], qr[1], pN1, 0, 0, 0); kf[2] = FA_KF(3, 0); kf[3] = FA_KF(3, 1); FA_EXP2(11, pC1, 6); FA_SB();
;         pN0 = __builtin_amdgcn_mfma_f32_32x32x16_bf16(kf[0], qr[2], pN0, 0, 0, 0); FA_EXP2(12, pC1, 8); FA_SB();
;         pN1 = __builtin_amdgcn_mfma_f32_32x32x16_bf16(kf[1], qr[2], pN1, 0, 0, 0); FA_EXP2(13, pC1, 10); FA_SB();
;         pN0 = __builtin_amdgcn_mfma_f32_32x32x16_bf16(kf[2], qr[3], pN0, 0, 0, 0); FA_EXP2(14, pC1, 12); FA_SB();
;         pN1 = __builtin_amdgcn_mfma_f32_32x32x16_bf16(kf[3], qr[3], pN1, 0, 0, 0); FA_EXP2(15, pC1, 14); FA_SB();
;     ...
;         lsum += ps; cbC = cbN;
;         if (i + 2 < NT) { *(FLAS u32x4*)(lds + LA_K + (i & 1) * KBUF + kdst) = kreg;
; #pragma unroll
;             for (int j = 0; j < 2; ++j) { *(FLAS u32x2*)(lds + LA_V + ((i + 2) & 3) * VBUF + vdst + j * 64 * VPITCH) = (u32x2){vreg[j].x, vreg[j].y}; *(FLAS u32x2*)(lds + LA_V + ((i + 2) & 3) * VBUF + vdst + j * 64 * VPITCH + 16) = (u32x2){vreg[j].z, vreg[j].w}; } }
.Lz_go_e:
	s_waitcnt lgkmcnt(2)
	v_mfma_f32_32x32x16_bf16 v[64:79], v[204:207], v[160:163], v[144:159]
	ds_read_b128 v[136:139], v250 offset:8192
	ds_read_b128 v[140:143], v250 offset:8704
	v_exp_f32_e32 v112, v112
	v_exp_f32_e32 v113, v113
	v_add_f32_e32 v212, v110, v212
	v_add_f32_e32 v212, v111, v212
	v_mfma_f32_32x32x16_bf16 v[80:95], v[200:203], v[160:163], v[144:159]
	v_exp_f32_e32 v114, v114
	v_exp_f32_e32 v115, v115
	s_branch .Lk2_e
.Lgather_e:
	v_add_u32_e32 v76, s49, v210
	v_add_u32_e32 v64, 0x17600, v76
	v_add_u32_e32 v66, 0x17680, v76
	v_add_u32_e32 v67, 0x17608, v76
	v_add_u32_e32 v68, 0x17688, v76
	ds_read2_b32 v[64:65], v64 offset1:1
	ds_read2_b32 v[80:81], v66 offset1:1
	ds_read2_b32 v[66:67], v67 offset1:1
	ds_read2_b32 v[82:83], v68 offset1:1
	v_add_u32_e32 v68, 0x17620, v76
	v_add_u32_e32 v70, 0x176a0, v76
	v_add_u32_e32 v71, 0x17628, v76
	v_add_u32_e32 v72, 0x176a8, v76
	ds_read2_b32 v[68:69], v68 offset1:1
	ds_read2_b32 v[84:85], v70 offset1:1
	ds_read2_b32 v[70:71], v71 offset1:1
	ds_read2_b32 v[86:87], v72 offset1:1
	v_add_u32_e32 v72, 0x17640, v76
	v_add_u32_e32 v74, 0x176c0, v76
	v_add_u32_e32 v75, 0x17648, v76
	v_add_u32_e32 v77, 0x176c8, v76
	ds_read2_b32 v[72:73], v72 offset1:1
	ds_read2_b32 v[88:89], v74 offset1:1
	ds_read2_b32 v[74:75], v75 offset1:1
	ds_read2_b32 v[90:91], v77 offset1:1
	v_add_u32_e32 v77, 0x17660, v76
	v_add_u32_e32 v78, 0x176e0, v76
	v_add_u32_e32 v79, 0x17668, v76
	v_add_u32_e32 v94, 0x176e8, v76
	ds_read2_b32 v[76:77], v77 offset1:1
	ds_read2_b32 v[92:93], v78 offset1:1
	ds_read2_b32 v[78:79], v79 offset1:1
	ds_read2_b32 v[94:95], v94 offset1:1
	s_waitcnt lgkmcnt(0)
	v_sub_f32_e32 v64, v64, v211
	v_sub_f32_e32 v65, v65, v211
	v_sub_f32_e32 v66, v66, v211
	v_sub_f32_e32 v67, v67, v211
	v_sub_f32_e32 v68, v68, v211
	v_sub_f32_e32 v69, v69, v211
	v_sub_f32_e32 v70, v70, v211
	v_sub_f32_e32 v71, v71, v211
	v_sub_f32_e32 v72, v72, v211
	v_sub_f32_e32 v73, v73, v211
	v_sub_f32_e32 v74, v74, v211
	v_sub_f32_e32 v75, v75, v211
	v_sub_f32_e32 v76, v76, v211
	v_sub_f32_e32 v77, v77, v211
	v_sub_f32_e32 v78, v78, v211
	v_sub_f32_e32 v79, v79, v211
	v_sub_f32_e32 v80, v80, v211
	v_sub_f32_e32 v81, v81, v211
	v_sub_f32_e32 v82, v82, v211
	v_sub_f32_e32 v83, v83, v211
	v_sub_f32_e32 v84, v84, v211
	v_sub_f32_e32 v85, v85, v211
	v_sub_f32_e32 v86, v86, v211
	v_sub_f32_e32 v87, v87, v211
	v_sub_f32_e32 v88, v88, v211
	v_sub_f32_e32 v89, v89, v211
	v_sub_f32_e32 v90, v90, v211
	v_sub_f32_e32 v91, v91, v211
	v_sub_f32_e32 v92, v92, v211
	v_sub_f32_e32 v93, v93, v211
	v_sub_f32_e32 v94, v94, v211
	v_sub_f32_e32 v95, v95, v211
	s_nop 1
	v_mfma_f32_32x32x16_bf16 v[64:79], v[204:207], v[160:163], v[64:79]
	ds_read_b128 v[136:139], v250 offset:8192
	ds_read_b128 v[140:143], v250 offset:8704
	v_exp_f32_e32 v112, v112
	v_exp_f32_e32 v113, v113
	v_add_f32_e32 v212, v110, v212
	v_add_f32_e32 v212, v111, v212
	v_mfma_f32_32x32x16_bf16 v[80:95], v[200:203], v[160:163], v[80:95]
	v_exp_f32_e32 v114, v114
	v_exp_f32_e32 v115, v115
.Lk2_e:
	s_add_i32 s34, s19, 2
	v_mfma_f32_32x32x16_bf16 v[64:79], v[196:199], v[164:167], v[64:79]
	v_exp_f32_e32 v116, v116
	v_exp_f32_e32 v117, v117
	v_mfma_f32_32x32x16_bf16 v[80:95], v[192:195], v[164:167], v[80:95]
	v_exp_f32_e32 v118, v118
	v_exp_f32_e32 v119, v119
	s_waitcnt lgkmcnt(2)
	v_mfma_f32_32x32x16_bf16 v[64:79], v[128:131], v[168:171], v[64:79]
	v_exp_f32_e32 v120, v120
	v_exp_f32_e32 v121, v121
	s_waitcnt lgkmcnt(2)
	v_mfma_f32_32x32x16_bf16 v[80:95], v[132:135], v[168:171], v[80:95]
	v_exp_f32_e32 v122, v122
	v_exp_f32_e32 v123, v123
	s_waitcnt lgkmcnt(1)
	v_mfma_f32_32x32x16_bf16 v[64:79], v[136:139], v[172:175], v[64:79]
	v_exp_f32_e32 v124, v124
	v_exp_f32_e32 v125, v125
	s_waitcnt lgkmcnt(0)
	v_mfma_f32_32x32x16_bf16 v[80:95], v[140:143], v[172:175], v[80:95]
	v_exp_f32_e32 v126, v126
	v_exp_f32_e32 v127, v127
	s_andn2_b64 vcc, exec, s[0:1]
	s_cbranch_vccnz .LBB0_456
	s_and_b32 s0, s34, 2
	s_mulk_i32 s0, 0x4800
	v_add_u32_e32 v128, s0, v245
	v_add_u32_e32 v129, 0x4000, v128
	v_add_u32_e32 v128, 0x6000, v128
	s_waitcnt vmcnt(2)
	ds_write_b128 v225, v[176:179]
	s_waitcnt vmcnt(1)
	ds_write2_b64 v129, v[180:181], v[182:183] offset1:2
	s_waitcnt vmcnt(0)
	ds_write2_b64 v128, v[184:185], v[186:187] offset0:128 offset1:130

; #define FA_SB() __builtin_amdgcn_sched_barrier(0)
; #define FA_PVM(G) do { o[(G) & 3] = __builtin_amdgcn_mfma_f32_32x32x16_bf16(__builtin_bit_cast(bf16x8, vr[(G) % 3]), __builtin_bit_cast(bf16x8, PWC[(G) >> 2]), o[(G) & 3], 0, 0, 0); if ((G) + 3 < 16) vr[(G) % 3] = FA_VFRAG((G) + 3); } while (0)
; #define FA_EXP2(J, PX, R) do { const float e0_ = __builtin_amdgcn_exp2f(PX[R]), e1_ = __builtin_amdgcn_exp2f(PX[(R) + 1]); ps += e0_; ps += e1_; PWN[(J) >> 2][(J) & 3] = cvtpk(e0_, e1_); } while (0)
; __device__ __forceinline__ void attn_unit_a(FLAS unsigned char* lds, const Unit u) {
;     ...
;         for (int g = 8; g < 16; ++g) { FA_PVM(g); FA_EXP2(g - 8, pC0, 2 * (g - 8));
;             if (g == 12) { kf[0] = FA_KF(0, 0); kf[1] = FA_KF(0, 1); kf[2] = FA_KF(1, 0); kf[3] = FA_KF(1, 1); }
;             FA_SB(); }
;         float cbN; bool ziN; const int inx = (i + 1 < NT) ? i + 1 : NT - 1;
;         FA_BIAS(inx, pN0, pN1, cbN, ziN);
.LBB0_462:
	s_waitcnt lgkmcnt(2)
	v_mfma_f32_32x32x16_bf16 v[48:63], v[136:139], v[140:143], v[48:63]
	ds_read_b128 v[136:139], v201 offset:30272
	v_exp_f32_e32 v64, v64
	v_exp_f32_e32 v65, v65
	v_cvt_pk_bf16_f32 v232, v120, v121
	v_cvt_pk_bf16_f32 v233, v122, v123
	s_waitcnt lgkmcnt(2)
	v_mfma_f32_32x32x16_bf16 v[32:47], v[128:131], v[140:143], v[32:47]
	ds_read_b128 v[128:131], v201 offset:16480
	v_exp_f32_e32 v66, v66
	v_exp_f32_e32 v67, v67
	v_add_f32_e32 v212, v64, v212
	v_add_f32_e32 v212, v65, v212
	v_cvt_pk_bf16_f32 v234, v124, v125
	v_cvt_pk_bf16_f32 v235, v126, v127
	s_waitcnt lgkmcnt(2)
	v_mfma_f32_32x32x16_bf16 v[16:31], v[132:135], v[140:143], v[16:31]
	ds_read_b128 v[132:135], v201 offset:21088
	v_exp_f32_e32 v68, v68
	v_exp_f32_e32 v69, v69
	v_add_f32_e32 v212, v66, v212
	v_add_f32_e32 v212, v67, v212
	s_waitcnt lgkmcnt(2)
	v_mfma_f32_32x32x16_bf16 v[0:15], v[136:139], v[140:143], v[0:15]
	ds_read_b128 v[136:139], v201 offset:25696
	v_exp_f32_e32 v70, v70
	v_exp_f32_e32 v71, v71
	v_add_f32_e32 v212, v68, v212
	v_add_f32_e32 v212, v69, v212
	s_waitcnt lgkmcnt(2)
	v_mfma_f32_32x32x16_bf16 v[48:63], v[128:131], v[232:235], v[48:63]
	ds_read_b128 v[128:131], v201 offset:30304
	ds_read_b128 v[200:203], v247
	ds_read_b128 v[196:199], v247 offset:512
	ds_read_b128 v[192:195], v248
	ds_read_b128 v[188:191], v248 offset:512
	v_exp_f32_e32 v72, v72
	v_exp_f32_e32 v73, v73
	v_add_f32_e32 v212, v70, v212
	v_add_f32_e32 v212, v71, v212
	s_waitcnt lgkmcnt(6)
	v_mfma_f32_32x32x16_bf16 v[32:47], v[132:135], v[232:235], v[32:47]
	v_exp_f32_e32 v74, v74
	v_exp_f32_e32 v75, v75
	v_add_f32_e32 v212, v72, v212
	v_add_f32_e32 v212, v73, v212
	s_waitcnt lgkmcnt(5)
	v_mfma_f32_32x32x16_bf16 v[16:31], v[136:139], v[232:235], v[16:31]
	v_exp_f32_e32 v76, v76
	v_exp_f32_e32 v77, v77
	v_add_f32_e32 v212, v74, v212
	v_add_f32_e32 v212, v75, v212
	s_waitcnt lgkmcnt(4)
	v_mfma_f32_32x32x16_bf16 v[0:15], v[128:131], v[232:235], v[0:15]
	v_exp_f32_e32 v78, v78
	v_exp_f32_e32 v79, v79
	v_add_f32_e32 v212, v76, v212
	v_add_f32_e32 v212, v77, v212
	ds_read_b128 v[128:131], v249
	ds_read_b128 v[132:135], v249 offset:512
	s_min_u32 s12, s34, 0x7f
	s_lshl_b32 s12, s12, 6
	s_sub_i32 s14, s12, s47
	s_sub_i32 s15, s14, 31
	s_cmpk_lt_i32 s15, 0x22f
	s_cbranch_scc0 .Lz_plus_o
	s_cmpk_gt_i32 s14, 0xfd92
	s_cbranch_scc1 .Lgather_o
	v_sub_f32_e32 v126, s100, v211
	s_branch .Lz_chk_o

; #define FLAS __attribute__((address_space(3)))
; #define FA_SB() __builtin_amdgcn_sched_barrier(0)
; #define FA_EXP2(J, PX, R) do { const float e0_ = __builtin_amdgcn_exp2f(PX[R]), e1_ = __builtin_amdgcn_exp2f(PX[(R) + 1]); ps += e0_; ps += e1_; PWN[(J) >> 2][(J) & 3] = cvtpk(e0_, e1_); } while (0)
; __device__ __forceinline__ void attn_unit_a(FLAS unsigned char* lds, const Unit u) {
;     ...
;         FA_BIAS(inx, pN0, pN1, cbN, ziN);
;         FA_SB();
;         if (ziN) { pN0 = __builtin_amdgcn_mfma_f32_32x32x16_bf16(kf[0], qr[0], z16, 0, 0, 0); FA_EXP2(8, pC1, 0); FA_SB(); pN1 = __builtin_amdgcn_mfma_f32_32x32x16_bf16(kf[1], qr[0], z16, 0, 0, 0); }
;         else { pN0 = __builtin_amdgcn_mfma_f32_32x32x16_bf16(kf[0], qr[0], pN0, 0, 0, 0); FA_EXP2(8, pC1, 0); FA_SB(); pN1 = __builtin_amdgcn_mfma_f32_32x32x16_bf16(kf[1], qr[0], pN1, 0, 0, 0); }
;         kf[0] = FA_KF(2, 0); kf[1] = FA_KF(2, 1); FA_EXP2(9, pC1, 2); FA_SB();
;         pN0 = __builtin_amdgcn_mfma_f32_32x32x16_bf16(kf[2], qr[1], pN0, 0, 0, 0); FA_EXP2(10, pC1, 4); FA_SB();
;         pN1 = __builtin_amdgcn_mfma_f32_32x32x16_bf16(kf[3], qr[1], pN1, 0, 0, 0); kf[2] = FA_KF(3, 0); kf[3] = FA_KF(3, 1); FA_EXP2(11, pC1, 6); FA_SB();
;         pN0 = __builtin_amdgcn_mfma_f32_32x32x16_bf16(kf[0], qr[2], pN0, 0, 0, 0); FA_EXP2(12, pC1, 8); FA_SB();
;         pN1 = __builtin_amdgcn_mfma_f32_32x32x16_bf16(kf[1], qr[2], pN1, 0, 0, 0); FA_EXP2(13, pC1, 10); FA_SB();
;         pN0 = __builtin_amdgcn_mfma_f32_32x32x16_bf16(kf[2], qr[3], pN0, 0, 0, 0); FA_EXP2(14, pC1, 12); FA_SB();
;         pN1 = __builtin_amdgcn_mfma_f32_32x32x16_bf16(kf[3], qr[3], pN1, 0, 0, 0); FA_EXP2(15, pC1, 14); FA_SB();
;     ...
;         lsum += ps; cbC = cbN;
;         if (i + 2 < NT) { *(FLAS u32x4*)(lds + LA_K + (i & 1) * KBUF + kdst) = kreg;
; #pragma unroll
;             for (int j = 0; j < 2; ++j) { *(FLAS u32x2*)(lds + LA_V + ((i + 2) & 3) * VBUF + vdst + j * 64 * VPITCH) = (u32x2){vreg[j].x, vreg[j].y}; *(FLAS u32x2*)(lds + LA_V + ((i + 2) & 3) * VBUF + vdst + j * 64 * VPITCH + 16) = (u32x2){vreg[j].z, vreg[j].w}; } }
.Lz_go_o:
	s_waitcnt lgkmcnt(2)
	v_mfma_f32_32x32x16_bf16 v[96:111], v[200:203], v[160:163], v[144:159]
	ds_read_b128 v[136:139], v250
	ds_read_b128 v[140:143], v250 offset:512
	v_exp_f32_e32 v80, v80
	v_exp_f32_e32 v81, v81
	v_add_f32_e32 v212, v78, v212
	v_add_f32_e32 v212, v79, v212
	v_mfma_f32_32x32x16_bf16 v[112:127], v[196:199], v[160:163], v[144:159]
	v_exp_f32_e32 v82, v82
	v_exp_f32_e32 v83, v83
	s_branch .Lk2_o
.Lgather_o:
	v_sub_u32_e32 v96, s12, v244
	v_lshl_add_u32 v108, v96, 2, v240
	v_add_u32_e32 v96, 0x1500, v108
	v_add_u32_e32 v98, 0x1580, v108
	v_add_u32_e32 v99, 0x1508, v108
	v_add_u32_e32 v100, 0x1588, v108
	ds_read2_b32 v[96:97], v96 offset1:1
	ds_read2_b32 v[112:113], v98 offset1:1
	ds_read2_b32 v[98:99], v99 offset1:1
	ds_read2_b32 v[114:115], v100 offset1:1
	v_add_u32_e32 v100, 0x1520, v108
	v_add_u32_e32 v102, 0x15a0, v108
	v_add_u32_e32 v103, 0x1528, v108
	v_add_u32_e32 v104, 0x15a8, v108
	ds_read2_b32 v[100:101], v100 offset1:1
	ds_read2_b32 v[116:117], v102 offset1:1
	ds_read2_b32 v[102:103], v103 offset1:1
	ds_read2_b32 v[118:119], v104 offset1:1
	v_add_u32_e32 v104, 0x1540, v108
	v_add_u32_e32 v106, 0x15c0, v108
	v_add_u32_e32 v107, 0x1548, v108
	v_add_u32_e32 v109, 0x15c8, v108
	ds_read2_b32 v[104:105], v104 offset1:1
	ds_read2_b32 v[120:121], v106 offset1:1
	ds_read2_b32 v[106:107], v107 offset1:1
	ds_read2_b32 v[122:123], v109 offset1:1
	v_add_u32_e32 v109, 0x1560, v108
	v_add_u32_e32 v110, 0x15e0, v108
	v_add_u32_e32 v111, 0x1568, v108
	v_add_u32_e32 v126, 0x15e8, v108
	ds_read2_b32 v[108:109], v109 offset1:1
	ds_read2_b32 v[124:125], v110 offset1:1
	ds_read2_b32 v[110:111], v111 offset1:1
	ds_read2_b32 v[126:127], v126 offset1:1
	s_waitcnt lgkmcnt(0)
	v_sub_f32_e32 v96, v96, v211
	v_sub_f32_e32 v97, v97, v211
	v_sub_f32_e32 v98, v98, v211
	v_sub_f32_e32 v99, v99, v211
	v_sub_f32_e32 v100, v100, v211
	v_sub_f32_e32 v101, v101, v211
	v_sub_f32_e32 v102, v102, v211
	v_sub_f32_e32 v103, v103, v211
	v_sub_f32_e32 v104, v104, v211
	v_sub_f32_e32 v105, v105, v211
	v_sub_f32_e32 v106, v106, v211
	v_sub_f32_e32 v107, v107, v211
	v_sub_f32_e32 v108, v108, v211
	v_sub_f32_e32 v109, v109, v211
	v_sub_f32_e32 v110, v110, v211
	v_sub_f32_e32 v111, v111, v211
	v_sub_f32_e32 v112, v112, v211
	v_sub_f32_e32 v113, v113, v211
	v_sub_f32_e32 v114, v114, v211
	v_sub_f32_e32 v115, v115, v211
	v_sub_f32_e32 v116, v116, v211
	v_sub_f32_e32 v117, v117, v211
	v_sub_f32_e32 v118, v118, v211
	v_sub_f32_e32 v119, v119, v211
	v_sub_f32_e32 v120, v120, v211
	v_sub_f32_e32 v121, v121, v211
	v_sub_f32_e32 v122, v122, v211
	v_sub_f32_e32 v123, v123, v211
	v_sub_f32_e32 v124, v124, v211
	v_sub_f32_e32 v125, v125, v211
	v_sub_f32_e32 v126, v126, v211
	v_sub_f32_e32 v127, v127, v211
	s_nop 1
	v_mfma_f32_32x32x16_bf16 v[96:111], v[200:203], v[160:163], v[96:111]
	ds_read_b128 v[136:139], v250
	ds_read_b128 v[140:143], v250 offset:512
	v_exp_f32_e32 v80, v80
	v_exp_f32_e32 v81, v81
	v_add_f32_e32 v212, v78, v212
	v_add_f32_e32 v212, v79, v212
	v_mfma_f32_32x32x16_bf16 v[112:127], v[196:199], v[160:163], v[112:127]
	v_exp_f32_e32 v82, v82
	v_exp_f32_e32 v83, v83
.Lk2_o:
	v_mfma_f32_32x32x16_bf16 v[96:111], v[192:195], v[164:167], v[96:111]
	v_exp_f32_e32 v84, v84
	v_exp_f32_e32 v85, v85
	v_mfma_f32_32x32x16_bf16 v[112:127], v[188:191], v[164:167], v[112:127]
	v_exp_f32_e32 v86, v86
	v_exp_f32_e32 v87, v87
	s_waitcnt lgkmcnt(2)
	v_mfma_f32_32x32x16_bf16 v[96:111], v[128:131], v[168:171], v[96:111]
	v_exp_f32_e32 v88, v88
	v_exp_f32_e32 v89, v89
	s_waitcnt lgkmcnt(2)
	v_mfma_f32_32x32x16_bf16 v[112:127], v[132:135], v[168:171], v[112:127]
	v_exp_f32_e32 v90, v90
	v_exp_f32_e32 v91, v91
	s_waitcnt lgkmcnt(1)
	v_mfma_f32_32x32x16_bf16 v[96:111], v[136:139], v[172:175], v[96:111]
	v_exp_f32_e32 v92, v92
	v_exp_f32_e32 v93, v93
	s_waitcnt lgkmcnt(0)
	v_mfma_f32_32x32x16_bf16 v[112:127], v[140:143], v[172:175], v[112:127]
	v_exp_f32_e32 v94, v94
	v_exp_f32_e32 v95, v95
	s_andn2_b64 vcc, exec, s[20:21]
	s_cbranch_vccnz .LBB0_476
	v_add_u32_e32 v128, s18, v245
	v_add_u32_e32 v129, 0x4000, v128
	v_add_u32_e32 v128, 0x6000, v128
	s_waitcnt vmcnt(2)
	ds_write_b128 v225, v[176:179] offset:8192
	s_waitcnt vmcnt(1)
	ds_write2_b64 v129, v[180:181], v[182:183] offset1:2
	s_waitcnt vmcnt(0)
	ds_write2_b64 v128, v[184:185], v[186:187] offset0:128 offset1:130
